# swiglu epilogue: rstd LDS reads software-pipelined over 3 register quads (counted lgkmcnt) on top of K-loop loader VALU elimination
# speedup vs baseline: 1.0009x; 1.0009x over previous
.LBB0_531:
	v_lshl_add_u32 v154, s54, 12, v145
	ds_read_b128 v[96:99], v154
	ds_read_b128 v[156:159], v154 offset:256
	ds_read_b128 v[234:237], v154 offset:512
	s_waitcnt lgkmcnt(2)
	v_mov_b32_e32 v150, v97
	v_mov_b32_e32 v151, v98
	v_mov_b32_e32 v97, v99
	v_pk_add_f32 v[96:97], v[150:151], v[96:97]
	v_lshl_add_u32 v151, s24, 8, v139
	v_add_f32_e32 v96, v96, v97
	v_fmamk_f32 v96, v96, 0x3a800000, v229
	v_rsq_f32_e32 v150, v96
	ds_read_b128 v[96:99], v154 offset:768
	v_pk_mul_f32 v[128:129], v[128:129], v[150:151] op_sel_hi:[1,0]
	v_pk_mul_f32 v[124:125], v[124:125], v[150:151] op_sel_hi:[1,0]
	s_waitcnt lgkmcnt(2)
	v_mov_b32_e32 v152, v157
	v_mov_b32_e32 v153, v158
	v_mov_b32_e32 v157, v159
	v_pk_add_f32 v[156:157], v[152:153], v[156:157]
	v_pk_mul_f32 v[124:125], v[124:125], v[128:129]
	v_add_f32_e32 v156, v156, v157
	v_fmamk_f32 v156, v156, 0x3a800000, v229
	v_rsq_f32_e32 v148, v156
	ds_read_b128 v[156:159], v154 offset:2048
	v_pk_mul_f32 v[128:129], v[128:129], s[68:69] op_sel_hi:[1,0]
	v_pk_mul_f32 v[126:127], v[126:127], v[150:151] op_sel_hi:[1,0]
	v_exp_f32_e32 v128, v128
	v_exp_f32_e32 v129, v129
	s_waitcnt lgkmcnt(2)
	v_mov_b32_e32 v152, v235
	v_mov_b32_e32 v153, v236
	v_mov_b32_e32 v235, v237
	v_pk_add_f32 v[234:235], v[152:153], v[234:235]
	v_pk_add_f32 v[128:129], v[128:129], 1.0 op_sel_hi:[1,0]
	v_add_f32_e32 v234, v234, v235
	v_fmamk_f32 v234, v234, 0x3a800000, v229
	v_rsq_f32_e32 v146, v234
	ds_read_b128 v[234:237], v154 offset:2304
	v_rcp_f32_e32 v128, v128
	v_rcp_f32_e32 v129, v129
	v_pk_mul_f32 v[120:121], v[120:121], v[150:151] op_sel_hi:[1,0]
	v_pk_mul_f32 v[116:117], v[116:117], v[150:151] op_sel_hi:[1,0]
	s_waitcnt lgkmcnt(2)
	v_mov_b32_e32 v152, v97
	v_mov_b32_e32 v153, v98
	v_mov_b32_e32 v97, v99
	v_pk_add_f32 v[96:97], v[152:153], v[96:97]
	v_pk_mul_f32 v[124:125], v[124:125], v[128:129]
	v_add_f32_e32 v96, v96, v97
	v_fmamk_f32 v96, v96, 0x3a800000, v229
	v_rsq_f32_e32 v144, v96
	ds_read_b128 v[96:99], v154 offset:2560
	v_pk_mul_f32 v[128:129], v[130:131], v[150:151] op_sel_hi:[1,0]
	v_pk_mul_f32 v[116:117], v[120:121], v[116:117]
	v_pk_mul_f32 v[126:127], v[128:129], v[126:127]
	v_pk_mul_f32 v[128:129], v[128:129], s[68:69] op_sel_hi:[1,0]
	s_waitcnt lgkmcnt(2)
	v_mov_b32_e32 v152, v157
	v_mov_b32_e32 v153, v158
	v_mov_b32_e32 v157, v159
	v_pk_add_f32 v[156:157], v[152:153], v[156:157]
	v_pk_mul_f32 v[120:121], v[120:121], s[68:69] op_sel_hi:[1,0]
	v_add_f32_e32 v156, v156, v157
	v_fmamk_f32 v156, v156, 0x3a800000, v229
	v_rsq_f32_e32 v142, v156
	ds_read_b128 v[156:159], v154 offset:2816
	v_exp_f32_e32 v128, v128
	v_exp_f32_e32 v129, v129
	v_exp_f32_e32 v120, v120
	v_exp_f32_e32 v121, v121
	s_waitcnt lgkmcnt(2)
	v_mov_b32_e32 v152, v235
	v_mov_b32_e32 v153, v236
	v_mov_b32_e32 v235, v237
	v_pk_add_f32 v[234:235], v[152:153], v[234:235]
	v_pk_mul_f32 v[112:113], v[112:113], v[148:149] op_sel_hi:[1,0]
	v_add_f32_e32 v234, v234, v235
	v_fmamk_f32 v234, v234, 0x3a800000, v229
	v_rsq_f32_e32 v140, v234
	v_pk_mul_f32 v[108:109], v[108:109], v[148:149] op_sel_hi:[1,0]
	v_pk_add_f32 v[128:129], v[128:129], 1.0 op_sel_hi:[1,0]
	v_pk_mul_f32 v[108:109], v[108:109], v[112:113]
	v_pk_mul_f32 v[112:113], v[112:113], s[68:69] op_sel_hi:[1,0]
	v_pk_add_f32 v[120:121], v[120:121], 1.0 op_sel_hi:[1,0]
	v_exp_f32_e32 v112, v112
	v_exp_f32_e32 v113, v113
	v_rcp_f32_e32 v128, v128
	v_rcp_f32_e32 v129, v129
	v_rcp_f32_e32 v120, v120
	v_rcp_f32_e32 v121, v121
	s_waitcnt lgkmcnt(1)
	v_mov_b32_e32 v152, v97
	v_mov_b32_e32 v153, v98
	v_mov_b32_e32 v97, v99
	v_pk_add_f32 v[96:97], v[152:153], v[96:97]
	v_pk_add_f32 v[112:113], v[112:113], 1.0 op_sel_hi:[1,0]
	v_add_f32_e32 v96, v96, v97
	v_fmamk_f32 v96, v96, 0x3a800000, v229
	v_pk_mul_f32 v[126:127], v[126:127], v[128:129]
	v_pk_mul_f32 v[116:117], v[116:117], v[120:121]
	v_rcp_f32_e32 v112, v112
	v_rcp_f32_e32 v113, v113
	v_rsq_f32_e32 v138, v96
	v_cvt_pk_bf16_f32 v124, v124, v125
	v_cvt_pk_bf16_f32 v125, v126, v127
	v_cvt_pk_bf16_f32 v126, v116, v117
	v_pk_mul_f32 v[116:117], v[122:123], v[150:151] op_sel_hi:[1,0]
	v_pk_mul_f32 v[118:119], v[118:119], v[150:151] op_sel_hi:[1,0]
	v_pk_mul_f32 v[108:109], v[108:109], v[112:113]
	v_pk_mul_f32 v[118:119], v[116:117], v[118:119]
	v_pk_mul_f32 v[116:117], v[116:117], s[68:69] op_sel_hi:[1,0]
	v_pk_mul_f32 v[112:113], v[114:115], v[148:149] op_sel_hi:[1,0]
	v_exp_f32_e32 v116, v116
	v_exp_f32_e32 v117, v117
	v_pk_mul_f32 v[110:111], v[110:111], v[148:149] op_sel_hi:[1,0]
	v_pk_mul_f32 v[104:105], v[104:105], v[148:149] op_sel_hi:[1,0]
	v_pk_mul_f32 v[100:101], v[100:101], v[148:149] op_sel_hi:[1,0]
	v_pk_mul_f32 v[110:111], v[112:113], v[110:111]
	v_pk_mul_f32 v[112:113], v[112:113], s[68:69] op_sel_hi:[1,0]
	v_pk_mul_f32 v[100:101], v[104:105], v[100:101]
	v_pk_mul_f32 v[104:105], v[104:105], s[68:69] op_sel_hi:[1,0]
	v_exp_f32_e32 v112, v112
	v_exp_f32_e32 v113, v113
	v_exp_f32_e32 v104, v104
	v_exp_f32_e32 v105, v105
	v_pk_add_f32 v[116:117], v[116:117], 1.0 op_sel_hi:[1,0]
	v_pk_mul_f32 v[92:93], v[92:93], v[146:147] op_sel_hi:[1,0]
	v_rcp_f32_e32 v116, v116
	v_rcp_f32_e32 v117, v117
	v_pk_mul_f32 v[88:89], v[88:89], v[146:147] op_sel_hi:[1,0]
	v_pk_add_f32 v[112:113], v[112:113], 1.0 op_sel_hi:[1,0]
	v_pk_mul_f32 v[88:89], v[88:89], v[92:93]
	v_pk_mul_f32 v[92:93], v[92:93], s[68:69] op_sel_hi:[1,0]
	v_pk_add_f32 v[104:105], v[104:105], 1.0 op_sel_hi:[1,0]
	v_exp_f32_e32 v92, v92
	v_exp_f32_e32 v93, v93
	v_rcp_f32_e32 v112, v112
	v_rcp_f32_e32 v113, v113
	v_rcp_f32_e32 v104, v104
	v_rcp_f32_e32 v105, v105
	v_lshl_or_b32 v152, s1, 7, v147
	v_pk_mul_f32 v[116:117], v[118:119], v[116:117]
	v_ashrrev_i32_e32 v153, 31, v152
	v_cvt_pk_bf16_f32 v127, v116, v117
	v_mov_b64_e32 v[116:117], s[8:9]
	v_mad_i64_i32 v[120:121], s[0:1], v151, s42, v[116:117]
	v_lshlrev_b64 v[118:119], 1, v[152:153]
	v_pk_add_f32 v[92:93], v[92:93], 1.0 op_sel_hi:[1,0]
	v_lshl_add_u64 v[120:121], v[120:121], 0, v[118:119]
	v_pk_mul_f32 v[110:111], v[110:111], v[112:113]
	v_pk_mul_f32 v[100:101], v[100:101], v[104:105]
	v_rcp_f32_e32 v92, v92
	v_rcp_f32_e32 v93, v93
	global_store_dwordx4 v[120:121], v[124:127], off
	v_cvt_pk_bf16_f32 v108, v108, v109
	v_cvt_pk_bf16_f32 v109, v110, v111
	v_cvt_pk_bf16_f32 v110, v100, v101
	v_pk_mul_f32 v[100:101], v[106:107], v[148:149] op_sel_hi:[1,0]
	v_pk_mul_f32 v[102:103], v[102:103], v[148:149] op_sel_hi:[1,0]
	v_pk_mul_f32 v[88:89], v[88:89], v[92:93]
	v_pk_mul_f32 v[102:103], v[100:101], v[102:103]
	v_pk_mul_f32 v[100:101], v[100:101], s[68:69] op_sel_hi:[1,0]
	v_pk_mul_f32 v[92:93], v[94:95], v[146:147] op_sel_hi:[1,0]
	v_exp_f32_e32 v100, v100
	v_exp_f32_e32 v101, v101
	v_pk_mul_f32 v[90:91], v[90:91], v[146:147] op_sel_hi:[1,0]
	v_pk_mul_f32 v[84:85], v[84:85], v[146:147] op_sel_hi:[1,0]
	v_pk_mul_f32 v[80:81], v[80:81], v[146:147] op_sel_hi:[1,0]
	v_pk_mul_f32 v[90:91], v[92:93], v[90:91]
	v_pk_mul_f32 v[92:93], v[92:93], s[68:69] op_sel_hi:[1,0]
	v_pk_mul_f32 v[80:81], v[84:85], v[80:81]
	v_pk_mul_f32 v[84:85], v[84:85], s[68:69] op_sel_hi:[1,0]
	v_exp_f32_e32 v92, v92
	v_exp_f32_e32 v93, v93
	v_exp_f32_e32 v84, v84
	v_exp_f32_e32 v85, v85
	v_pk_add_f32 v[100:101], v[100:101], 1.0 op_sel_hi:[1,0]
	v_pk_mul_f32 v[76:77], v[76:77], v[144:145] op_sel_hi:[1,0]
	v_rcp_f32_e32 v100, v100
	v_rcp_f32_e32 v101, v101
	v_pk_mul_f32 v[72:73], v[72:73], v[144:145] op_sel_hi:[1,0]
	v_pk_add_f32 v[92:93], v[92:93], 1.0 op_sel_hi:[1,0]
	v_pk_mul_f32 v[72:73], v[72:73], v[76:77]
	v_pk_mul_f32 v[76:77], v[76:77], s[68:69] op_sel_hi:[1,0]
	v_pk_add_f32 v[84:85], v[84:85], 1.0 op_sel_hi:[1,0]
	v_exp_f32_e32 v76, v76
	v_exp_f32_e32 v77, v77
	v_rcp_f32_e32 v92, v92
	v_rcp_f32_e32 v93, v93
	v_rcp_f32_e32 v84, v84
	v_rcp_f32_e32 v85, v85
	v_pk_mul_f32 v[100:101], v[102:103], v[100:101]
	v_pk_add_f32 v[76:77], v[76:77], 1.0 op_sel_hi:[1,0]
	v_cvt_pk_bf16_f32 v111, v100, v101
	v_or_b32_e32 v100, 16, v151
	v_mad_i64_i32 v[100:101], s[0:1], v100, s42, v[116:117]
	v_lshl_add_u64 v[100:101], v[100:101], 0, v[118:119]
	v_pk_mul_f32 v[90:91], v[90:91], v[92:93]
	v_pk_mul_f32 v[80:81], v[80:81], v[84:85]
	v_rcp_f32_e32 v76, v76
	v_rcp_f32_e32 v77, v77
	global_store_dwordx4 v[100:101], v[108:111], off
	v_cvt_pk_bf16_f32 v88, v88, v89
	v_cvt_pk_bf16_f32 v89, v90, v91
	v_cvt_pk_bf16_f32 v90, v80, v81
	v_pk_mul_f32 v[80:81], v[86:87], v[146:147] op_sel_hi:[1,0]
	v_pk_mul_f32 v[82:83], v[82:83], v[146:147] op_sel_hi:[1,0]
	v_pk_mul_f32 v[72:73], v[72:73], v[76:77]
	v_pk_mul_f32 v[82:83], v[80:81], v[82:83]
	v_pk_mul_f32 v[80:81], v[80:81], s[68:69] op_sel_hi:[1,0]
	v_pk_mul_f32 v[76:77], v[78:79], v[144:145] op_sel_hi:[1,0]
	v_exp_f32_e32 v80, v80
	v_exp_f32_e32 v81, v81
	v_pk_mul_f32 v[74:75], v[74:75], v[144:145] op_sel_hi:[1,0]
	v_pk_mul_f32 v[68:69], v[68:69], v[144:145] op_sel_hi:[1,0]
	v_pk_mul_f32 v[64:65], v[64:65], v[144:145] op_sel_hi:[1,0]
	v_pk_mul_f32 v[74:75], v[76:77], v[74:75]
	v_pk_mul_f32 v[76:77], v[76:77], s[68:69] op_sel_hi:[1,0]
	v_pk_mul_f32 v[64:65], v[68:69], v[64:65]
	v_pk_mul_f32 v[68:69], v[68:69], s[68:69] op_sel_hi:[1,0]
	v_exp_f32_e32 v76, v76
	v_exp_f32_e32 v77, v77
	v_exp_f32_e32 v68, v68
	v_exp_f32_e32 v69, v69
	v_pk_add_f32 v[80:81], v[80:81], 1.0 op_sel_hi:[1,0]
	v_pk_add_f32 v[76:77], v[76:77], 1.0 op_sel_hi:[1,0]
	v_rcp_f32_e32 v80, v80
	v_rcp_f32_e32 v81, v81
	v_pk_add_f32 v[68:69], v[68:69], 1.0 op_sel_hi:[1,0]
	v_rcp_f32_e32 v76, v76
	v_rcp_f32_e32 v77, v77
	v_rcp_f32_e32 v68, v68
	v_rcp_f32_e32 v69, v69
	v_pk_mul_f32 v[80:81], v[82:83], v[80:81]
	v_pk_mul_f32 v[74:75], v[74:75], v[76:77]
	v_cvt_pk_bf16_f32 v91, v80, v81
	v_or_b32_e32 v80, 32, v151
	v_mad_i64_i32 v[80:81], s[0:1], v80, s42, v[116:117]
	v_lshl_add_u64 v[80:81], v[80:81], 0, v[118:119]
	v_pk_mul_f32 v[64:65], v[64:65], v[68:69]
	global_store_dwordx4 v[80:81], v[88:91], off
	v_cvt_pk_bf16_f32 v72, v72, v73
	v_cvt_pk_bf16_f32 v73, v74, v75
	v_cvt_pk_bf16_f32 v74, v64, v65
	v_pk_mul_f32 v[64:65], v[70:71], v[144:145] op_sel_hi:[1,0]
	v_pk_mul_f32 v[66:67], v[66:67], v[144:145] op_sel_hi:[1,0]
	s_nop 0
	v_pk_mul_f32 v[66:67], v[64:65], v[66:67]
	v_pk_mul_f32 v[64:65], v[64:65], s[68:69] op_sel_hi:[1,0]
	s_nop 0
	v_exp_f32_e32 v64, v64
	v_exp_f32_e32 v65, v65
	s_nop 0
	v_pk_add_f32 v[64:65], v[64:65], 1.0 op_sel_hi:[1,0]
	s_nop 0
	v_rcp_f32_e32 v64, v64
	v_rcp_f32_e32 v65, v65
	s_nop 0
	v_pk_mul_f32 v[64:65], v[66:67], v[64:65]
	s_nop 0
	v_cvt_pk_bf16_f32 v75, v64, v65
	v_or_b32_e32 v64, 48, v151
	v_mad_i64_i32 v[64:65], s[0:1], v64, s42, v[116:117]
	v_lshl_add_u64 v[64:65], v[64:65], 0, v[118:119]
	global_store_dwordx4 v[64:65], v[72:75], off
	v_add_u32_e32 v64, 0x80, v151
	v_pk_mul_f32 v[60:61], v[60:61], v[142:143] op_sel_hi:[1,0]
	v_pk_mul_f32 v[56:57], v[56:57], v[142:143] op_sel_hi:[1,0]
	v_pk_mul_f32 v[58:59], v[58:59], v[142:143] op_sel_hi:[1,0]
	v_pk_mul_f32 v[56:57], v[60:61], v[56:57]
	v_pk_mul_f32 v[60:61], v[60:61], s[68:69] op_sel_hi:[1,0]
	v_pk_mul_f32 v[52:53], v[52:53], v[142:143] op_sel_hi:[1,0]
	v_exp_f32_e32 v60, v60
	v_exp_f32_e32 v61, v61
	v_pk_mul_f32 v[48:49], v[48:49], v[142:143] op_sel_hi:[1,0]
	v_pk_mul_f32 v[44:45], v[44:45], v[140:141] op_sel_hi:[1,0]
	v_pk_mul_f32 v[48:49], v[52:53], v[48:49]
	v_pk_add_f32 v[60:61], v[60:61], 1.0 op_sel_hi:[1,0]
	v_pk_mul_f32 v[52:53], v[52:53], s[68:69] op_sel_hi:[1,0]
	v_rcp_f32_e32 v60, v60
	v_rcp_f32_e32 v61, v61
	v_exp_f32_e32 v52, v52
	v_exp_f32_e32 v53, v53
	v_pk_mul_f32 v[40:41], v[40:41], v[140:141] op_sel_hi:[1,0]
	v_pk_mul_f32 v[56:57], v[56:57], v[60:61]
	v_pk_mul_f32 v[60:61], v[62:63], v[142:143] op_sel_hi:[1,0]
	v_pk_mul_f32 v[40:41], v[40:41], v[44:45]
	v_pk_mul_f32 v[58:59], v[60:61], v[58:59]
	v_pk_mul_f32 v[60:61], v[60:61], s[68:69] op_sel_hi:[1,0]
	v_pk_mul_f32 v[44:45], v[44:45], s[68:69] op_sel_hi:[1,0]
	v_exp_f32_e32 v60, v60
	v_exp_f32_e32 v61, v61
	v_exp_f32_e32 v44, v44
	v_exp_f32_e32 v45, v45
	v_pk_add_f32 v[52:53], v[52:53], 1.0 op_sel_hi:[1,0]
	v_pk_add_f32 v[60:61], v[60:61], 1.0 op_sel_hi:[1,0]
	v_rcp_f32_e32 v52, v52
	v_rcp_f32_e32 v60, v60
	v_rcp_f32_e32 v61, v61
	v_rcp_f32_e32 v53, v53
	v_pk_add_f32 v[44:45], v[44:45], 1.0 op_sel_hi:[1,0]
	v_cvt_pk_bf16_f32 v56, v56, v57
	v_pk_mul_f32 v[58:59], v[58:59], v[60:61]
	v_rcp_f32_e32 v44, v44
	v_rcp_f32_e32 v45, v45
	v_pk_mul_f32 v[48:49], v[48:49], v[52:53]
	v_cvt_pk_bf16_f32 v57, v58, v59
	v_pk_mul_f32 v[50:51], v[50:51], v[142:143] op_sel_hi:[1,0]
	v_cvt_pk_bf16_f32 v58, v48, v49
	v_pk_mul_f32 v[48:49], v[54:55], v[142:143] op_sel_hi:[1,0]
	v_pk_mul_f32 v[40:41], v[40:41], v[44:45]
	v_pk_mul_f32 v[50:51], v[48:49], v[50:51]
	v_pk_mul_f32 v[48:49], v[48:49], s[68:69] op_sel_hi:[1,0]
	v_pk_mul_f32 v[44:45], v[46:47], v[140:141] op_sel_hi:[1,0]
	v_exp_f32_e32 v48, v48
	v_exp_f32_e32 v49, v49
	v_pk_mul_f32 v[42:43], v[42:43], v[140:141] op_sel_hi:[1,0]
	v_pk_mul_f32 v[36:37], v[36:37], v[140:141] op_sel_hi:[1,0]
	v_pk_mul_f32 v[32:33], v[32:33], v[140:141] op_sel_hi:[1,0]
	v_pk_mul_f32 v[42:43], v[44:45], v[42:43]
	v_pk_mul_f32 v[44:45], v[44:45], s[68:69] op_sel_hi:[1,0]
	v_pk_mul_f32 v[32:33], v[36:37], v[32:33]
	v_pk_mul_f32 v[36:37], v[36:37], s[68:69] op_sel_hi:[1,0]
	v_exp_f32_e32 v44, v44
	v_exp_f32_e32 v45, v45
	v_exp_f32_e32 v36, v36
	v_exp_f32_e32 v37, v37
	v_pk_add_f32 v[48:49], v[48:49], 1.0 op_sel_hi:[1,0]
	v_pk_mul_f32 v[28:29], v[28:29], v[138:139] op_sel_hi:[1,0]
	v_pk_mul_f32 v[24:25], v[24:25], v[138:139] op_sel_hi:[1,0]
	v_rcp_f32_e32 v48, v48
	v_rcp_f32_e32 v49, v49
	v_pk_mul_f32 v[24:25], v[24:25], v[28:29]
	v_pk_mul_f32 v[28:29], v[28:29], s[68:69] op_sel_hi:[1,0]
	v_pk_add_f32 v[44:45], v[44:45], 1.0 op_sel_hi:[1,0]
	v_pk_add_f32 v[36:37], v[36:37], 1.0 op_sel_hi:[1,0]
	v_exp_f32_e32 v28, v28
	v_exp_f32_e32 v29, v29
	v_rcp_f32_e32 v44, v44
	v_rcp_f32_e32 v45, v45
	v_rcp_f32_e32 v36, v36
	v_rcp_f32_e32 v37, v37
	v_pk_mul_f32 v[48:49], v[50:51], v[48:49]
	v_pk_add_f32 v[28:29], v[28:29], 1.0 op_sel_hi:[1,0]
	v_cvt_pk_bf16_f32 v59, v48, v49
	v_mad_i64_i32 v[48:49], s[0:1], v64, s42, v[116:117]
	v_lshl_add_u64 v[48:49], v[48:49], 0, v[118:119]
	v_pk_mul_f32 v[42:43], v[42:43], v[44:45]
	v_pk_mul_f32 v[32:33], v[32:33], v[36:37]
	v_rcp_f32_e32 v28, v28
	v_rcp_f32_e32 v29, v29
	global_store_dwordx4 v[48:49], v[56:59], off
	v_cvt_pk_bf16_f32 v40, v40, v41
	v_cvt_pk_bf16_f32 v41, v42, v43
	v_cvt_pk_bf16_f32 v42, v32, v33
	v_pk_mul_f32 v[32:33], v[38:39], v[140:141] op_sel_hi:[1,0]
	v_pk_mul_f32 v[34:35], v[34:35], v[140:141] op_sel_hi:[1,0]
	v_pk_mul_f32 v[24:25], v[24:25], v[28:29]
	v_pk_mul_f32 v[34:35], v[32:33], v[34:35]
	v_pk_mul_f32 v[32:33], v[32:33], s[68:69] op_sel_hi:[1,0]
	v_pk_mul_f32 v[28:29], v[30:31], v[138:139] op_sel_hi:[1,0]
	v_exp_f32_e32 v32, v32
	v_exp_f32_e32 v33, v33
	v_pk_mul_f32 v[26:27], v[26:27], v[138:139] op_sel_hi:[1,0]
	v_pk_mul_f32 v[20:21], v[20:21], v[138:139] op_sel_hi:[1,0]
	v_pk_mul_f32 v[16:17], v[16:17], v[138:139] op_sel_hi:[1,0]
	v_pk_mul_f32 v[26:27], v[28:29], v[26:27]
	v_pk_mul_f32 v[28:29], v[28:29], s[68:69] op_sel_hi:[1,0]
	v_pk_mul_f32 v[16:17], v[20:21], v[16:17]
	v_pk_mul_f32 v[20:21], v[20:21], s[68:69] op_sel_hi:[1,0]
	v_exp_f32_e32 v28, v28
	v_exp_f32_e32 v29, v29
	v_exp_f32_e32 v20, v20
	v_exp_f32_e32 v21, v21
	v_pk_add_f32 v[32:33], v[32:33], 1.0 op_sel_hi:[1,0]
	v_pk_add_f32 v[28:29], v[28:29], 1.0 op_sel_hi:[1,0]
	v_rcp_f32_e32 v32, v32
	v_rcp_f32_e32 v33, v33
	v_pk_add_f32 v[20:21], v[20:21], 1.0 op_sel_hi:[1,0]
	v_rcp_f32_e32 v28, v28
	v_rcp_f32_e32 v29, v29
	v_rcp_f32_e32 v20, v20
	v_rcp_f32_e32 v21, v21
	v_pk_mul_f32 v[32:33], v[34:35], v[32:33]
	v_pk_mul_f32 v[26:27], v[26:27], v[28:29]
	v_cvt_pk_bf16_f32 v43, v32, v33
	v_add_u32_e32 v32, 0x90, v151
	v_mad_i64_i32 v[32:33], s[0:1], v32, s42, v[116:117]
	v_lshl_add_u64 v[32:33], v[32:33], 0, v[118:119]
	v_pk_mul_f32 v[16:17], v[16:17], v[20:21]
	global_store_dwordx4 v[32:33], v[40:43], off
	v_cvt_pk_bf16_f32 v24, v24, v25
	v_cvt_pk_bf16_f32 v25, v26, v27
	v_cvt_pk_bf16_f32 v26, v16, v17
	v_pk_mul_f32 v[16:17], v[22:23], v[138:139] op_sel_hi:[1,0]
	v_pk_mul_f32 v[18:19], v[18:19], v[138:139] op_sel_hi:[1,0]
	s_mov_b64 s[24:25], -1
	v_pk_mul_f32 v[18:19], v[16:17], v[18:19]
	v_pk_mul_f32 v[16:17], v[16:17], s[68:69] op_sel_hi:[1,0]
	s_andn2_b64 vcc, exec, s[4:5]
	v_exp_f32_e32 v16, v16
	v_exp_f32_e32 v17, v17
	s_nop 0
	v_pk_add_f32 v[16:17], v[16:17], 1.0 op_sel_hi:[1,0]
	s_nop 0
	v_rcp_f32_e32 v16, v16
	v_rcp_f32_e32 v17, v17
	s_nop 0
	v_pk_mul_f32 v[16:17], v[18:19], v[16:17]
	s_nop 0
	v_cvt_pk_bf16_f32 v27, v16, v17
	v_add_u32_e32 v16, 0xa0, v151
	v_mad_i64_i32 v[16:17], s[0:1], v16, s42, v[116:117]
	v_lshl_add_u64 v[16:17], v[16:17], 0, v[118:119]
	global_store_dwordx4 v[16:17], v[24:27], off
	s_waitcnt lgkmcnt(0)
	v_mov_b32_e32 v16, v157
	v_mov_b32_e32 v17, v158
	v_mov_b32_e32 v157, v159
	v_pk_add_f32 v[16:17], v[16:17], v[156:157]
	s_nop 0
	v_add_f32_e32 v16, v16, v17
	v_fmamk_f32 v16, v16, 0x3a800000, v229
	v_rsq_f32_e32 v16, v16
	s_nop 0
	v_pk_mul_f32 v[12:13], v[12:13], v[16:17] op_sel_hi:[1,0]
	v_pk_mul_f32 v[8:9], v[8:9], v[16:17] op_sel_hi:[1,0]
	v_pk_mul_f32 v[10:11], v[10:11], v[16:17] op_sel_hi:[1,0]
	v_pk_mul_f32 v[8:9], v[8:9], v[12:13]
	v_pk_mul_f32 v[12:13], v[12:13], s[68:69] op_sel_hi:[1,0]
	v_pk_mul_f32 v[4:5], v[4:5], v[16:17] op_sel_hi:[1,0]
	v_exp_f32_e32 v12, v12
	v_exp_f32_e32 v13, v13
	v_pk_mul_f32 v[0:1], v[0:1], v[16:17] op_sel_hi:[1,0]
	v_pk_mul_f32 v[2:3], v[2:3], v[16:17] op_sel_hi:[1,0]
	v_pk_mul_f32 v[0:1], v[4:5], v[0:1]
	v_pk_add_f32 v[12:13], v[12:13], 1.0 op_sel_hi:[1,0]
	v_pk_mul_f32 v[4:5], v[4:5], s[68:69] op_sel_hi:[1,0]
	v_rcp_f32_e32 v12, v12
	v_rcp_f32_e32 v13, v13
	v_exp_f32_e32 v4, v4
	v_exp_f32_e32 v5, v5
	v_pk_mul_f32 v[8:9], v[8:9], v[12:13]
	v_pk_mul_f32 v[12:13], v[14:15], v[16:17] op_sel_hi:[1,0]
	v_pk_add_f32 v[4:5], v[4:5], 1.0 op_sel_hi:[1,0]
	v_pk_mul_f32 v[10:11], v[12:13], v[10:11]
	v_pk_mul_f32 v[12:13], v[12:13], s[68:69] op_sel_hi:[1,0]
	v_rcp_f32_e32 v4, v4
	v_exp_f32_e32 v12, v12
	v_exp_f32_e32 v13, v13
	v_rcp_f32_e32 v5, v5
	v_cvt_pk_bf16_f32 v8, v8, v9
	v_pk_add_f32 v[12:13], v[12:13], 1.0 op_sel_hi:[1,0]
	s_nop 0
	v_rcp_f32_e32 v12, v12
	v_rcp_f32_e32 v13, v13
	v_pk_mul_f32 v[0:1], v[0:1], v[4:5]
	v_pk_mul_f32 v[10:11], v[10:11], v[12:13]
	s_nop 0
	v_cvt_pk_bf16_f32 v9, v10, v11
	v_cvt_pk_bf16_f32 v10, v0, v1
	v_pk_mul_f32 v[0:1], v[6:7], v[16:17] op_sel_hi:[1,0]
	s_nop 0
	v_pk_mul_f32 v[2:3], v[0:1], v[2:3]
	v_pk_mul_f32 v[0:1], v[0:1], s[68:69] op_sel_hi:[1,0]
	s_nop 0
	v_exp_f32_e32 v0, v0
	v_exp_f32_e32 v1, v1
	s_nop 0
	v_pk_add_f32 v[0:1], v[0:1], 1.0 op_sel_hi:[1,0]
	s_nop 0
	v_rcp_f32_e32 v0, v0
	v_rcp_f32_e32 v1, v1
	s_nop 0
	v_pk_mul_f32 v[0:1], v[2:3], v[0:1]
	s_nop 0
	v_cvt_pk_bf16_f32 v11, v0, v1
	v_add_u32_e32 v0, 0xb0, v151
	v_mad_i64_i32 v[0:1], s[0:1], v0, s42, v[116:117]
	v_lshl_add_u64 v[0:1], v[0:1], 0, v[118:119]
	global_store_dwordx4 v[0:1], v[8:11], off
	s_cbranch_vccnz .LBB0_522
	s_andn2_b64 vcc, exec, s[6:7]
	s_cbranch_vccnz .LBB0_521
	s_barrier
	s_branch .LBB0_521
